# P12: epilogue column-shift/rstd operands requested in the last K-iteration of the 4-phase loop (epilogue head = register copies, no vmcnt(0) on the serialized unit boundary)
# baseline (speedup 1.0000x reference)
.LBB0_3264:
	s_ashr_i32 s11, s10, 31
	v_cmp_lt_i64_e32 vcc, s[12:13], v[162:163]
	s_lshl_b64 s[12:13], s[10:11], 19
	s_add_u32 s12, s36, s12
	s_addc_u32 s13, s37, s13
	s_and_b64 s[14:15], vcc, exec
	s_cselect_b32 s11, s13, s25
	s_cselect_b32 s57, s12, s24
	s_ashr_i32 s9, s8, 31
	s_lshl_b64 s[14:15], s[8:9], 19
	s_add_u32 s14, s38, s14
	s_addc_u32 s15, s39, s15
	s_and_b64 s[18:19], vcc, exec
	s_cselect_b32 s9, s15, s35
	s_cselect_b32 s60, s14, s34
	s_add_u32 s24, s24, 0x40080
	s_addc_u32 s25, s25, 0
	s_add_u32 s61, s34, 0x100
	s_addc_u32 s62, s35, 0
	s_mov_b32 s63, -2
	ds_read_b128 v[130:133], v171
	ds_read_b128 v[134:137], v171 offset:1024
	ds_read_b128 v[138:141], v171 offset:2048
	ds_read_b128 v[142:145], v171 offset:3072
	s_add_u32 s18, s24, 0xfffc0080
	s_addc_u32 s19, s25, -1
	s_cmp_eq_u32 s63, 12
	s_cselect_b32 s19, s11, s19
	s_cselect_b32 s18, s57, s18
	s_cselect_b32 s35, s9, s62
	s_cselect_b32 s34, s60, s61
	v_lshl_add_u64 v[174:175], s[24:25], 0, v[158:159]
	s_add_i32 m0, s43, 0xc000
	ds_read_b128 v[166:169], v173
	ds_read_b128 v[178:181], v173 offset:1024
	ds_read_b128 v[182:185], v173 offset:2048
	ds_read_b128 v[186:189], v173 offset:3072
	ds_read_b128 v[190:193], v173 offset:4096
	ds_read_b128 v[194:197], v173 offset:5120
	ds_read_b128 v[198:201], v173 offset:6144
	ds_read_b128 v[202:205], v173 offset:7168
	global_load_lds_dwordx4 v[174:175], off
	v_lshl_add_u64 v[174:175], s[24:25], 0, v[160:161]
	s_add_i32 m0, s43, 0xe000
	s_nop 0
	global_load_lds_dwordx4 v[174:175], off
	ds_read_b128 v[206:209], v177
	ds_read_b128 v[210:213], v177 offset:1024
	ds_read_b128 v[214:217], v177 offset:2048
	ds_read_b128 v[218:221], v177 offset:3072
	s_waitcnt lgkmcnt(0)
	s_setprio 1
	s_barrier
	v_mfma_f32_16x16x32_bf16 v[126:129], v[130:133], v[166:169], 0
	v_mfma_f32_16x16x32_bf16 v[122:125], v[138:141], v[166:169], 0
	v_mfma_f32_16x16x32_bf16 v[110:113], v[130:133], v[182:185], 0
	v_mfma_f32_16x16x32_bf16 v[106:109], v[138:141], v[182:185], 0
	v_mfma_f32_16x16x32_bf16 v[94:97], v[130:133], v[190:193], 0
	v_mfma_f32_16x16x32_bf16 v[90:93], v[138:141], v[190:193], 0
	v_mfma_f32_16x16x32_bf16 v[78:81], v[130:133], v[198:201], 0
	v_mfma_f32_16x16x32_bf16 v[74:77], v[138:141], v[198:201], 0
	v_mfma_f32_16x16x32_bf16 v[126:129], v[134:137], v[178:181], v[126:129]
	v_mfma_f32_16x16x32_bf16 v[122:125], v[142:145], v[178:181], v[122:125]
	v_mfma_f32_16x16x32_bf16 v[110:113], v[134:137], v[186:189], v[110:113]
	v_mfma_f32_16x16x32_bf16 v[106:109], v[142:145], v[186:189], v[106:109]
	v_mfma_f32_16x16x32_bf16 v[94:97], v[134:137], v[194:197], v[94:97]
	v_mfma_f32_16x16x32_bf16 v[90:93], v[142:145], v[194:197], v[90:93]
	v_mfma_f32_16x16x32_bf16 v[78:81], v[134:137], v[202:205], v[78:81]
	v_mfma_f32_16x16x32_bf16 v[74:77], v[142:145], v[202:205], v[74:77]
	v_mfma_f32_16x16x32_bf16 v[118:121], v[206:209], v[166:169], 0
	v_mfma_f32_16x16x32_bf16 v[114:117], v[214:217], v[166:169], 0
	v_mfma_f32_16x16x32_bf16 v[102:105], v[206:209], v[182:185], 0
	v_mfma_f32_16x16x32_bf16 v[98:101], v[214:217], v[182:185], 0
	v_mfma_f32_16x16x32_bf16 v[86:89], v[206:209], v[190:193], 0
	v_mfma_f32_16x16x32_bf16 v[82:85], v[214:217], v[190:193], 0
	v_mfma_f32_16x16x32_bf16 v[70:73], v[206:209], v[198:201], 0
	v_mfma_f32_16x16x32_bf16 v[66:69], v[214:217], v[198:201], 0
	v_mfma_f32_16x16x32_bf16 v[118:121], v[210:213], v[178:181], v[118:121]
	v_mfma_f32_16x16x32_bf16 v[114:117], v[218:221], v[178:181], v[114:117]
	v_mfma_f32_16x16x32_bf16 v[102:105], v[210:213], v[186:189], v[102:105]
	v_mfma_f32_16x16x32_bf16 v[98:101], v[218:221], v[186:189], v[98:101]
	v_mfma_f32_16x16x32_bf16 v[86:89], v[210:213], v[194:197], v[86:89]
	v_mfma_f32_16x16x32_bf16 v[82:85], v[218:221], v[194:197], v[82:85]
	v_mfma_f32_16x16x32_bf16 v[70:73], v[210:213], v[202:205], v[70:73]
	v_mfma_f32_16x16x32_bf16 v[66:69], v[218:221], v[202:205], v[66:69]
	s_barrier
	s_setprio 0
	s_add_i32 s20, s54, s42
	v_lshl_add_u64 v[174:175], s[34:35], 0, v[150:151]
	s_mov_b32 m0, s20
	s_nop 0
	global_load_lds_dwordx4 v[174:175], off
	v_lshl_add_u64 v[222:223], s[34:35], 0, v[146:147]
	s_add_i32 m0, s20, 0x2000
	s_nop 0
	global_load_lds_dwordx4 v[222:223], off
	s_mov_b32 m0, s43
	v_lshl_add_u64 v[224:225], s[18:19], 0, v[152:153]
	ds_read_b128 v[166:169], v173 offset:16384
	ds_read_b128 v[178:181], v173 offset:17408
	ds_read_b128 v[182:185], v173 offset:18432
	ds_read_b128 v[186:189], v173 offset:19456
	ds_read_b128 v[190:193], v173 offset:20480
	ds_read_b128 v[194:197], v173 offset:21504
	ds_read_b128 v[198:201], v173 offset:22528
	ds_read_b128 v[202:205], v173 offset:23552
	global_load_lds_dwordx4 v[224:225], off
	v_lshl_add_u64 v[226:227], s[18:19], 0, v[148:149]
	s_mov_b32 m0, s44
	s_nop 0
	global_load_lds_dwordx4 v[226:227], off
	s_waitcnt vmcnt(6)
	s_waitcnt lgkmcnt(0)
	s_setprio 1
	s_barrier
	v_mfma_f32_16x16x32_bf16 v[62:65], v[130:133], v[166:169], 0
	v_mfma_f32_16x16x32_bf16 v[58:61], v[138:141], v[166:169], 0
	v_mfma_f32_16x16x32_bf16 v[46:49], v[130:133], v[182:185], 0
	v_mfma_f32_16x16x32_bf16 v[42:45], v[138:141], v[182:185], 0
	v_mfma_f32_16x16x32_bf16 v[30:33], v[130:133], v[190:193], 0
	v_mfma_f32_16x16x32_bf16 v[26:29], v[138:141], v[190:193], 0
	v_mfma_f32_16x16x32_bf16 v[14:17], v[130:133], v[198:201], 0
	v_mfma_f32_16x16x32_bf16 v[10:13], v[138:141], v[198:201], 0
	v_mfma_f32_16x16x32_bf16 v[62:65], v[134:137], v[178:181], v[62:65]
	v_mfma_f32_16x16x32_bf16 v[58:61], v[142:145], v[178:181], v[58:61]
	v_mfma_f32_16x16x32_bf16 v[46:49], v[134:137], v[186:189], v[46:49]
	v_mfma_f32_16x16x32_bf16 v[42:45], v[142:145], v[186:189], v[42:45]
	v_mfma_f32_16x16x32_bf16 v[30:33], v[134:137], v[194:197], v[30:33]
	v_mfma_f32_16x16x32_bf16 v[26:29], v[142:145], v[194:197], v[26:29]
	v_mfma_f32_16x16x32_bf16 v[14:17], v[134:137], v[202:205], v[14:17]
	v_mfma_f32_16x16x32_bf16 v[10:13], v[142:145], v[202:205], v[10:13]
	v_mfma_f32_16x16x32_bf16 v[54:57], v[206:209], v[166:169], 0
	v_mfma_f32_16x16x32_bf16 v[50:53], v[214:217], v[166:169], 0
	v_mfma_f32_16x16x32_bf16 v[38:41], v[206:209], v[182:185], 0
	v_mfma_f32_16x16x32_bf16 v[34:37], v[214:217], v[182:185], 0
	v_mfma_f32_16x16x32_bf16 v[22:25], v[206:209], v[190:193], 0
	v_mfma_f32_16x16x32_bf16 v[18:21], v[214:217], v[190:193], 0
	v_mfma_f32_16x16x32_bf16 v[6:9], v[206:209], v[198:201], 0
	v_mfma_f32_16x16x32_bf16 v[2:5], v[214:217], v[198:201], 0
	v_mfma_f32_16x16x32_bf16 v[54:57], v[210:213], v[178:181], v[54:57]
	v_mfma_f32_16x16x32_bf16 v[50:53], v[218:221], v[178:181], v[50:53]
	v_mfma_f32_16x16x32_bf16 v[38:41], v[210:213], v[186:189], v[38:41]
	v_mfma_f32_16x16x32_bf16 v[34:37], v[218:221], v[186:189], v[34:37]
	v_mfma_f32_16x16x32_bf16 v[22:25], v[210:213], v[194:197], v[22:25]
	v_mfma_f32_16x16x32_bf16 v[18:21], v[218:221], v[194:197], v[18:21]
	v_mfma_f32_16x16x32_bf16 v[6:9], v[210:213], v[202:205], v[6:9]
	v_mfma_f32_16x16x32_bf16 v[2:5], v[218:221], v[202:205], v[2:5]
	s_barrier
	s_setprio 0
	s_add_u32 s20, s34, 0x40000
	s_addc_u32 s21, s35, 0
	s_add_i32 s64, s55, s42
	v_lshl_add_u64 v[252:253], s[20:21], 0, v[150:151]
	s_mov_b32 m0, s64
	s_nop 0
	global_load_lds_dwordx4 v[252:253], off
	v_lshl_add_u64 v[252:253], s[20:21], 0, v[146:147]
	s_add_i32 m0, s64, 0x2000
	s_nop 0
	global_load_lds_dwordx4 v[252:253], off
	s_add_i32 s20, 0, 0x18000
	v_add_u32_e32 v142, s20, v157
	ds_read_b128 v[130:133], v142
	ds_read_b128 v[134:137], v142 offset:1024
	ds_read_b128 v[138:141], v142 offset:2048
	ds_read_b128 v[142:145], v142 offset:3072
	s_add_u32 s18, s18, 0x40000
	s_addc_u32 s19, s19, 0
	s_mov_b32 m0, s45
	v_lshl_add_u64 v[206:207], s[18:19], 0, v[152:153]
	ds_read_b128 v[166:169], v173 offset:32768
	ds_read_b128 v[178:181], v173 offset:33792
	ds_read_b128 v[182:185], v173 offset:34816
	ds_read_b128 v[186:189], v173 offset:35840
	ds_read_b128 v[190:193], v173 offset:36864
	ds_read_b128 v[194:197], v173 offset:37888
	ds_read_b128 v[198:201], v173 offset:38912
	ds_read_b128 v[202:205], v173 offset:39936
	global_load_lds_dwordx4 v[206:207], off
	v_lshl_add_u64 v[206:207], s[18:19], 0, v[148:149]
	s_mov_b32 m0, s46
	s_nop 0
	global_load_lds_dwordx4 v[206:207], off
	s_add_i32 s21, 0, 0x1c000
	v_add_u32_e32 v154, s21, v157
	ds_read_b128 v[206:209], v154
	ds_read_b128 v[210:213], v154 offset:1024
	ds_read_b128 v[214:217], v154 offset:2048
	ds_read_b128 v[218:221], v154 offset:3072
	s_waitcnt vmcnt(8)
	s_waitcnt lgkmcnt(0)
	s_setprio 1
	s_barrier
	v_mfma_f32_16x16x32_bf16 v[126:129], v[130:133], v[166:169], v[126:129]
	v_mfma_f32_16x16x32_bf16 v[122:125], v[138:141], v[166:169], v[122:125]
	v_mfma_f32_16x16x32_bf16 v[110:113], v[130:133], v[182:185], v[110:113]
	v_mfma_f32_16x16x32_bf16 v[106:109], v[138:141], v[182:185], v[106:109]
	v_mfma_f32_16x16x32_bf16 v[94:97], v[130:133], v[190:193], v[94:97]
	v_mfma_f32_16x16x32_bf16 v[90:93], v[138:141], v[190:193], v[90:93]
	v_mfma_f32_16x16x32_bf16 v[78:81], v[130:133], v[198:201], v[78:81]
	v_mfma_f32_16x16x32_bf16 v[74:77], v[138:141], v[198:201], v[74:77]
	v_mfma_f32_16x16x32_bf16 v[126:129], v[134:137], v[178:181], v[126:129]
	v_mfma_f32_16x16x32_bf16 v[122:125], v[142:145], v[178:181], v[122:125]
	v_mfma_f32_16x16x32_bf16 v[110:113], v[134:137], v[186:189], v[110:113]
	v_mfma_f32_16x16x32_bf16 v[106:109], v[142:145], v[186:189], v[106:109]
	v_mfma_f32_16x16x32_bf16 v[94:97], v[134:137], v[194:197], v[94:97]
	v_mfma_f32_16x16x32_bf16 v[90:93], v[142:145], v[194:197], v[90:93]
	v_mfma_f32_16x16x32_bf16 v[78:81], v[134:137], v[202:205], v[78:81]
	v_mfma_f32_16x16x32_bf16 v[74:77], v[142:145], v[202:205], v[74:77]
	v_mfma_f32_16x16x32_bf16 v[118:121], v[206:209], v[166:169], v[118:121]
	v_mfma_f32_16x16x32_bf16 v[114:117], v[214:217], v[166:169], v[114:117]
	v_mfma_f32_16x16x32_bf16 v[102:105], v[206:209], v[182:185], v[102:105]
	v_mfma_f32_16x16x32_bf16 v[98:101], v[214:217], v[182:185], v[98:101]
	v_mfma_f32_16x16x32_bf16 v[86:89], v[206:209], v[190:193], v[86:89]
	v_mfma_f32_16x16x32_bf16 v[82:85], v[214:217], v[190:193], v[82:85]
	v_mfma_f32_16x16x32_bf16 v[70:73], v[206:209], v[198:201], v[70:73]
	v_mfma_f32_16x16x32_bf16 v[66:69], v[214:217], v[198:201], v[66:69]
	v_mfma_f32_16x16x32_bf16 v[118:121], v[210:213], v[178:181], v[118:121]
	v_mfma_f32_16x16x32_bf16 v[114:117], v[218:221], v[178:181], v[114:117]
	v_mfma_f32_16x16x32_bf16 v[102:105], v[210:213], v[186:189], v[102:105]
	v_mfma_f32_16x16x32_bf16 v[98:101], v[218:221], v[186:189], v[98:101]
	v_mfma_f32_16x16x32_bf16 v[86:89], v[210:213], v[194:197], v[86:89]
	v_mfma_f32_16x16x32_bf16 v[82:85], v[218:221], v[194:197], v[82:85]
	v_mfma_f32_16x16x32_bf16 v[70:73], v[210:213], v[202:205], v[70:73]
	v_mfma_f32_16x16x32_bf16 v[66:69], v[218:221], v[202:205], v[66:69]
	s_barrier
	s_setprio 0
	s_add_i32 s18, s20, s42
	v_lshl_add_u64 v[174:175], v[174:175], 0, s[6:7]
	s_mov_b32 m0, s18
	s_nop 0
	global_load_lds_dwordx4 v[174:175], off
	v_lshl_add_u64 v[174:175], v[222:223], 0, s[6:7]
	s_add_i32 m0, s18, 0x2000
	s_nop 0
	global_load_lds_dwordx4 v[174:175], off
	s_mov_b32 m0, s50
	v_lshl_add_u64 v[174:175], v[224:225], 0, s[6:7]
	ds_read_b128 v[166:169], v173 offset:49152
	ds_read_b128 v[178:181], v173 offset:50176
	ds_read_b128 v[182:185], v173 offset:51200
	ds_read_b128 v[186:189], v173 offset:52224
	ds_read_b128 v[190:193], v173 offset:53248
	ds_read_b128 v[194:197], v173 offset:54272
	ds_read_b128 v[198:201], v173 offset:55296
	ds_read_b128 v[202:205], v173 offset:56320
	global_load_lds_dwordx4 v[174:175], off
	v_lshl_add_u64 v[174:175], v[226:227], 0, s[6:7]
	s_mov_b32 m0, s51
	s_nop 0
	global_load_lds_dwordx4 v[174:175], off
	s_add_u32 s18, s34, 0x40080
	s_addc_u32 s19, s35, 0
	s_add_i32 s20, s21, s42
	v_lshl_add_u64 v[252:253], s[18:19], 0, v[150:151]
	s_mov_b32 m0, s20
	s_nop 0
	global_load_lds_dwordx4 v[252:253], off
	v_lshl_add_u64 v[252:253], s[18:19], 0, v[146:147]
	s_add_i32 m0, s20, 0x2000
	s_nop 0
	global_load_lds_dwordx4 v[252:253], off
	s_waitcnt vmcnt(6)
	s_waitcnt lgkmcnt(0)
	s_setprio 1
	s_barrier
	v_mfma_f32_16x16x32_bf16 v[62:65], v[130:133], v[166:169], v[62:65]
	v_mfma_f32_16x16x32_bf16 v[58:61], v[138:141], v[166:169], v[58:61]
	v_mfma_f32_16x16x32_bf16 v[46:49], v[130:133], v[182:185], v[46:49]
	v_mfma_f32_16x16x32_bf16 v[42:45], v[138:141], v[182:185], v[42:45]
	v_mfma_f32_16x16x32_bf16 v[30:33], v[130:133], v[190:193], v[30:33]
	v_mfma_f32_16x16x32_bf16 v[26:29], v[138:141], v[190:193], v[26:29]
	v_mfma_f32_16x16x32_bf16 v[14:17], v[130:133], v[198:201], v[14:17]
	v_mfma_f32_16x16x32_bf16 v[10:13], v[138:141], v[198:201], v[10:13]
	v_mfma_f32_16x16x32_bf16 v[62:65], v[134:137], v[178:181], v[62:65]
	v_mfma_f32_16x16x32_bf16 v[58:61], v[142:145], v[178:181], v[58:61]
	v_mfma_f32_16x16x32_bf16 v[46:49], v[134:137], v[186:189], v[46:49]
	v_mfma_f32_16x16x32_bf16 v[42:45], v[142:145], v[186:189], v[42:45]
	v_mfma_f32_16x16x32_bf16 v[30:33], v[134:137], v[194:197], v[30:33]
	v_mfma_f32_16x16x32_bf16 v[26:29], v[142:145], v[194:197], v[26:29]
	v_mfma_f32_16x16x32_bf16 v[14:17], v[134:137], v[202:205], v[14:17]
	v_mfma_f32_16x16x32_bf16 v[10:13], v[142:145], v[202:205], v[10:13]
	v_mfma_f32_16x16x32_bf16 v[54:57], v[206:209], v[166:169], v[54:57]
	v_mfma_f32_16x16x32_bf16 v[50:53], v[214:217], v[166:169], v[50:53]
	v_mfma_f32_16x16x32_bf16 v[38:41], v[206:209], v[182:185], v[38:41]
	v_mfma_f32_16x16x32_bf16 v[34:37], v[214:217], v[182:185], v[34:37]
	v_mfma_f32_16x16x32_bf16 v[22:25], v[206:209], v[190:193], v[22:25]
	v_mfma_f32_16x16x32_bf16 v[18:21], v[214:217], v[190:193], v[18:21]
	v_mfma_f32_16x16x32_bf16 v[6:9], v[206:209], v[198:201], v[6:9]
	v_mfma_f32_16x16x32_bf16 v[2:5], v[214:217], v[198:201], v[2:5]
	v_mfma_f32_16x16x32_bf16 v[54:57], v[210:213], v[178:181], v[54:57]
	v_mfma_f32_16x16x32_bf16 v[50:53], v[218:221], v[178:181], v[50:53]
	v_mfma_f32_16x16x32_bf16 v[38:41], v[210:213], v[186:189], v[38:41]
	v_mfma_f32_16x16x32_bf16 v[34:37], v[218:221], v[186:189], v[34:37]
	v_mfma_f32_16x16x32_bf16 v[22:25], v[210:213], v[194:197], v[22:25]
	v_mfma_f32_16x16x32_bf16 v[18:21], v[218:221], v[194:197], v[18:21]
	v_mfma_f32_16x16x32_bf16 v[6:9], v[210:213], v[202:205], v[6:9]
	v_mfma_f32_16x16x32_bf16 v[2:5], v[218:221], v[202:205], v[2:5]
	s_barrier
	s_setprio 0
	s_add_i32 s63, s63, 2
	s_add_u32 s24, s24, 0x100
	s_addc_u32 s25, s25, 0
	s_add_u32 s61, s61, 0x100
	s_addc_u32 s62, s62, 0
	s_cmp_gt_u32 s63, 13
.LBB0_3265:
	ds_read_b128 v[130:133], v171
	ds_read_b128 v[134:137], v171 offset:1024
	ds_read_b128 v[138:141], v171 offset:2048
	ds_read_b128 v[142:145], v171 offset:3072
	s_add_u32 s18, s24, 0xfffc0080
	s_addc_u32 s19, s25, -1
	s_cmp_eq_u32 s63, 12
	s_cselect_b32 s19, s11, s19
	s_cselect_b32 s18, s57, s18
	s_cselect_b32 s35, s9, s62
	s_cselect_b32 s34, s60, s61
	s_cbranch_scc0 .Lp12_nopf
	s_ashr_i32 s68, s16, 3
	s_mul_hi_i32 s69, s68, 0x5800
	s_mulk_i32 s68, 0x5800
	s_add_u32 s68, s48, s68
	s_addc_u32 s69, s49, s69
	s_lshl_b32 s70, s17, 8
	s_ashr_i32 s71, s70, 31
	s_lshl_b64 s[70:71], s[70:71], 2
	s_add_u32 s66, s68, s70
	s_addc_u32 s67, s69, s71
	v_lshlrev_b32_e32 v248, 2, v156
	v_lshl_add_u32 v255, s16, 8, v1
	v_lshlrev_b32_e32 v255, 2, v255
	global_load_dwordx4 v[236:239], v248, s[66:67]
	global_load_dwordx4 v[240:243], v248, s[66:67] offset:512
	global_load_dwordx4 v[244:247], v248, s[66:67] offset:16
	global_load_dwordx4 v[248:251], v248, s[66:67] offset:528
	global_load_dword v228, v255, s[4:5]
	global_load_dword v229, v255, s[4:5] offset:64
	global_load_dword v233, v255, s[4:5] offset:128
	global_load_dword v234, v255, s[4:5] offset:192
	global_load_dword v235, v255, s[4:5] offset:512
	global_load_dword v176, v255, s[4:5] offset:640
	global_load_dword v172, v255, s[4:5] offset:704
	global_load_dword v255, v255, s[4:5] offset:576
.Lp12_nopf:
	v_lshl_add_u64 v[174:175], s[24:25], 0, v[158:159]
	s_add_i32 m0, s43, 0xc000
	ds_read_b128 v[166:169], v173
	ds_read_b128 v[178:181], v173 offset:1024
	ds_read_b128 v[182:185], v173 offset:2048
	ds_read_b128 v[186:189], v173 offset:3072
	ds_read_b128 v[190:193], v173 offset:4096
	ds_read_b128 v[194:197], v173 offset:5120
	ds_read_b128 v[198:201], v173 offset:6144
	ds_read_b128 v[202:205], v173 offset:7168
	global_load_lds_dwordx4 v[174:175], off
	v_lshl_add_u64 v[174:175], s[24:25], 0, v[160:161]
	s_add_i32 m0, s43, 0xe000
	s_nop 0
	global_load_lds_dwordx4 v[174:175], off
	ds_read_b128 v[206:209], v177
	ds_read_b128 v[210:213], v177 offset:1024
	ds_read_b128 v[214:217], v177 offset:2048
	ds_read_b128 v[218:221], v177 offset:3072
	s_waitcnt lgkmcnt(0)
	s_setprio 1
	s_barrier
	v_mfma_f32_16x16x32_bf16 v[126:129], v[130:133], v[166:169], v[126:129]
	v_mfma_f32_16x16x32_bf16 v[122:125], v[138:141], v[166:169], v[122:125]
	v_mfma_f32_16x16x32_bf16 v[110:113], v[130:133], v[182:185], v[110:113]
	v_mfma_f32_16x16x32_bf16 v[106:109], v[138:141], v[182:185], v[106:109]
	v_mfma_f32_16x16x32_bf16 v[94:97], v[130:133], v[190:193], v[94:97]
	v_mfma_f32_16x16x32_bf16 v[90:93], v[138:141], v[190:193], v[90:93]
	v_mfma_f32_16x16x32_bf16 v[78:81], v[130:133], v[198:201], v[78:81]
	v_mfma_f32_16x16x32_bf16 v[74:77], v[138:141], v[198:201], v[74:77]
	v_mfma_f32_16x16x32_bf16 v[126:129], v[134:137], v[178:181], v[126:129]
	v_mfma_f32_16x16x32_bf16 v[122:125], v[142:145], v[178:181], v[122:125]
	v_mfma_f32_16x16x32_bf16 v[110:113], v[134:137], v[186:189], v[110:113]
	v_mfma_f32_16x16x32_bf16 v[106:109], v[142:145], v[186:189], v[106:109]
	v_mfma_f32_16x16x32_bf16 v[94:97], v[134:137], v[194:197], v[94:97]
	v_mfma_f32_16x16x32_bf16 v[90:93], v[142:145], v[194:197], v[90:93]
	v_mfma_f32_16x16x32_bf16 v[78:81], v[134:137], v[202:205], v[78:81]
	v_mfma_f32_16x16x32_bf16 v[74:77], v[142:145], v[202:205], v[74:77]
	v_mfma_f32_16x16x32_bf16 v[118:121], v[206:209], v[166:169], v[118:121]
	v_mfma_f32_16x16x32_bf16 v[114:117], v[214:217], v[166:169], v[114:117]
	v_mfma_f32_16x16x32_bf16 v[102:105], v[206:209], v[182:185], v[102:105]
	v_mfma_f32_16x16x32_bf16 v[98:101], v[214:217], v[182:185], v[98:101]
	v_mfma_f32_16x16x32_bf16 v[86:89], v[206:209], v[190:193], v[86:89]
	v_mfma_f32_16x16x32_bf16 v[82:85], v[214:217], v[190:193], v[82:85]
	v_mfma_f32_16x16x32_bf16 v[70:73], v[206:209], v[198:201], v[70:73]
	v_mfma_f32_16x16x32_bf16 v[66:69], v[214:217], v[198:201], v[66:69]
	v_mfma_f32_16x16x32_bf16 v[118:121], v[210:213], v[178:181], v[118:121]
	v_mfma_f32_16x16x32_bf16 v[114:117], v[218:221], v[178:181], v[114:117]
	v_mfma_f32_16x16x32_bf16 v[102:105], v[210:213], v[186:189], v[102:105]
	v_mfma_f32_16x16x32_bf16 v[98:101], v[218:221], v[186:189], v[98:101]
	v_mfma_f32_16x16x32_bf16 v[86:89], v[210:213], v[194:197], v[86:89]
	v_mfma_f32_16x16x32_bf16 v[82:85], v[218:221], v[194:197], v[82:85]
	v_mfma_f32_16x16x32_bf16 v[70:73], v[210:213], v[202:205], v[70:73]
	v_mfma_f32_16x16x32_bf16 v[66:69], v[218:221], v[202:205], v[66:69]
	s_barrier
	s_setprio 0
	s_add_i32 s20, s54, s42
	v_lshl_add_u64 v[174:175], s[34:35], 0, v[150:151]
	s_mov_b32 m0, s20
	s_nop 0
	global_load_lds_dwordx4 v[174:175], off
	v_lshl_add_u64 v[222:223], s[34:35], 0, v[146:147]
	s_add_i32 m0, s20, 0x2000
	s_nop 0
	global_load_lds_dwordx4 v[222:223], off
	s_mov_b32 m0, s43
	v_lshl_add_u64 v[224:225], s[18:19], 0, v[152:153]
	ds_read_b128 v[166:169], v173 offset:16384
	ds_read_b128 v[178:181], v173 offset:17408
	ds_read_b128 v[182:185], v173 offset:18432
	ds_read_b128 v[186:189], v173 offset:19456
	ds_read_b128 v[190:193], v173 offset:20480
	ds_read_b128 v[194:197], v173 offset:21504
	ds_read_b128 v[198:201], v173 offset:22528
	ds_read_b128 v[202:205], v173 offset:23552
	global_load_lds_dwordx4 v[224:225], off
	v_lshl_add_u64 v[226:227], s[18:19], 0, v[148:149]
	s_mov_b32 m0, s44
	s_nop 0
	global_load_lds_dwordx4 v[226:227], off
	s_waitcnt vmcnt(6)
	s_waitcnt lgkmcnt(0)
	s_setprio 1
	s_barrier
	v_mfma_f32_16x16x32_bf16 v[62:65], v[130:133], v[166:169], v[62:65]
	v_mfma_f32_16x16x32_bf16 v[58:61], v[138:141], v[166:169], v[58:61]
	v_mfma_f32_16x16x32_bf16 v[46:49], v[130:133], v[182:185], v[46:49]
	v_mfma_f32_16x16x32_bf16 v[42:45], v[138:141], v[182:185], v[42:45]
	v_mfma_f32_16x16x32_bf16 v[30:33], v[130:133], v[190:193], v[30:33]
	v_mfma_f32_16x16x32_bf16 v[26:29], v[138:141], v[190:193], v[26:29]
	v_mfma_f32_16x16x32_bf16 v[14:17], v[130:133], v[198:201], v[14:17]
	v_mfma_f32_16x16x32_bf16 v[10:13], v[138:141], v[198:201], v[10:13]
	v_mfma_f32_16x16x32_bf16 v[62:65], v[134:137], v[178:181], v[62:65]
	v_mfma_f32_16x16x32_bf16 v[58:61], v[142:145], v[178:181], v[58:61]
	v_mfma_f32_16x16x32_bf16 v[46:49], v[134:137], v[186:189], v[46:49]
	v_mfma_f32_16x16x32_bf16 v[42:45], v[142:145], v[186:189], v[42:45]
	v_mfma_f32_16x16x32_bf16 v[30:33], v[134:137], v[194:197], v[30:33]
	v_mfma_f32_16x16x32_bf16 v[26:29], v[142:145], v[194:197], v[26:29]
	v_mfma_f32_16x16x32_bf16 v[14:17], v[134:137], v[202:205], v[14:17]
	v_mfma_f32_16x16x32_bf16 v[10:13], v[142:145], v[202:205], v[10:13]
	v_mfma_f32_16x16x32_bf16 v[54:57], v[206:209], v[166:169], v[54:57]
	v_mfma_f32_16x16x32_bf16 v[50:53], v[214:217], v[166:169], v[50:53]
	v_mfma_f32_16x16x32_bf16 v[38:41], v[206:209], v[182:185], v[38:41]
	v_mfma_f32_16x16x32_bf16 v[34:37], v[214:217], v[182:185], v[34:37]
	v_mfma_f32_16x16x32_bf16 v[22:25], v[206:209], v[190:193], v[22:25]
	v_mfma_f32_16x16x32_bf16 v[18:21], v[214:217], v[190:193], v[18:21]
	v_mfma_f32_16x16x32_bf16 v[6:9], v[206:209], v[198:201], v[6:9]
	v_mfma_f32_16x16x32_bf16 v[2:5], v[214:217], v[198:201], v[2:5]
	v_mfma_f32_16x16x32_bf16 v[54:57], v[210:213], v[178:181], v[54:57]
	v_mfma_f32_16x16x32_bf16 v[50:53], v[218:221], v[178:181], v[50:53]
	v_mfma_f32_16x16x32_bf16 v[38:41], v[210:213], v[186:189], v[38:41]
	v_mfma_f32_16x16x32_bf16 v[34:37], v[218:221], v[186:189], v[34:37]
	v_mfma_f32_16x16x32_bf16 v[22:25], v[210:213], v[194:197], v[22:25]
	v_mfma_f32_16x16x32_bf16 v[18:21], v[218:221], v[194:197], v[18:21]
	v_mfma_f32_16x16x32_bf16 v[6:9], v[210:213], v[202:205], v[6:9]
	v_mfma_f32_16x16x32_bf16 v[2:5], v[218:221], v[202:205], v[2:5]
	s_barrier
	s_setprio 0
	s_add_u32 s20, s34, 0x40000
	s_addc_u32 s21, s35, 0
	s_add_i32 s64, s55, s42
	v_lshl_add_u64 v[252:253], s[20:21], 0, v[150:151]
	s_mov_b32 m0, s64
	s_nop 0
	global_load_lds_dwordx4 v[252:253], off
	v_lshl_add_u64 v[252:253], s[20:21], 0, v[146:147]
	s_add_i32 m0, s64, 0x2000
	s_nop 0
	global_load_lds_dwordx4 v[252:253], off
	s_add_i32 s20, 0, 0x18000
	v_add_u32_e32 v142, s20, v157
	ds_read_b128 v[130:133], v142
	ds_read_b128 v[134:137], v142 offset:1024
	ds_read_b128 v[138:141], v142 offset:2048
	ds_read_b128 v[142:145], v142 offset:3072
	s_add_u32 s18, s18, 0x40000
	s_addc_u32 s19, s19, 0
	s_mov_b32 m0, s45
	v_lshl_add_u64 v[206:207], s[18:19], 0, v[152:153]
	ds_read_b128 v[166:169], v173 offset:32768
	ds_read_b128 v[178:181], v173 offset:33792
	ds_read_b128 v[182:185], v173 offset:34816
	ds_read_b128 v[186:189], v173 offset:35840
	ds_read_b128 v[190:193], v173 offset:36864
	ds_read_b128 v[194:197], v173 offset:37888
	ds_read_b128 v[198:201], v173 offset:38912
	ds_read_b128 v[202:205], v173 offset:39936
	global_load_lds_dwordx4 v[206:207], off
	v_lshl_add_u64 v[206:207], s[18:19], 0, v[148:149]
	s_mov_b32 m0, s46
	s_nop 0
	global_load_lds_dwordx4 v[206:207], off
	s_add_i32 s21, 0, 0x1c000
	v_add_u32_e32 v154, s21, v157
	ds_read_b128 v[206:209], v154
	ds_read_b128 v[210:213], v154 offset:1024
	ds_read_b128 v[214:217], v154 offset:2048
	ds_read_b128 v[218:221], v154 offset:3072
	s_waitcnt vmcnt(8)
	s_waitcnt lgkmcnt(0)
	s_setprio 1
	s_barrier
	v_mfma_f32_16x16x32_bf16 v[126:129], v[130:133], v[166:169], v[126:129]
	v_mfma_f32_16x16x32_bf16 v[122:125], v[138:141], v[166:169], v[122:125]
	v_mfma_f32_16x16x32_bf16 v[110:113], v[130:133], v[182:185], v[110:113]
	v_mfma_f32_16x16x32_bf16 v[106:109], v[138:141], v[182:185], v[106:109]
	v_mfma_f32_16x16x32_bf16 v[94:97], v[130:133], v[190:193], v[94:97]
	v_mfma_f32_16x16x32_bf16 v[90:93], v[138:141], v[190:193], v[90:93]
	v_mfma_f32_16x16x32_bf16 v[78:81], v[130:133], v[198:201], v[78:81]
	v_mfma_f32_16x16x32_bf16 v[74:77], v[138:141], v[198:201], v[74:77]
	v_mfma_f32_16x16x32_bf16 v[126:129], v[134:137], v[178:181], v[126:129]
	v_mfma_f32_16x16x32_bf16 v[122:125], v[142:145], v[178:181], v[122:125]
	v_mfma_f32_16x16x32_bf16 v[110:113], v[134:137], v[186:189], v[110:113]
	v_mfma_f32_16x16x32_bf16 v[106:109], v[142:145], v[186:189], v[106:109]
	v_mfma_f32_16x16x32_bf16 v[94:97], v[134:137], v[194:197], v[94:97]
	v_mfma_f32_16x16x32_bf16 v[90:93], v[142:145], v[194:197], v[90:93]
	v_mfma_f32_16x16x32_bf16 v[78:81], v[134:137], v[202:205], v[78:81]
	v_mfma_f32_16x16x32_bf16 v[74:77], v[142:145], v[202:205], v[74:77]
	v_mfma_f32_16x16x32_bf16 v[118:121], v[206:209], v[166:169], v[118:121]
	v_mfma_f32_16x16x32_bf16 v[114:117], v[214:217], v[166:169], v[114:117]
	v_mfma_f32_16x16x32_bf16 v[102:105], v[206:209], v[182:185], v[102:105]
	v_mfma_f32_16x16x32_bf16 v[98:101], v[214:217], v[182:185], v[98:101]
	v_mfma_f32_16x16x32_bf16 v[86:89], v[206:209], v[190:193], v[86:89]
	v_mfma_f32_16x16x32_bf16 v[82:85], v[214:217], v[190:193], v[82:85]
	v_mfma_f32_16x16x32_bf16 v[70:73], v[206:209], v[198:201], v[70:73]
	v_mfma_f32_16x16x32_bf16 v[66:69], v[214:217], v[198:201], v[66:69]
	v_mfma_f32_16x16x32_bf16 v[118:121], v[210:213], v[178:181], v[118:121]
	v_mfma_f32_16x16x32_bf16 v[114:117], v[218:221], v[178:181], v[114:117]
	v_mfma_f32_16x16x32_bf16 v[102:105], v[210:213], v[186:189], v[102:105]
	v_mfma_f32_16x16x32_bf16 v[98:101], v[218:221], v[186:189], v[98:101]
	v_mfma_f32_16x16x32_bf16 v[86:89], v[210:213], v[194:197], v[86:89]
	v_mfma_f32_16x16x32_bf16 v[82:85], v[218:221], v[194:197], v[82:85]
	v_mfma_f32_16x16x32_bf16 v[70:73], v[210:213], v[202:205], v[70:73]
	v_mfma_f32_16x16x32_bf16 v[66:69], v[218:221], v[202:205], v[66:69]
	s_barrier
	s_setprio 0
	s_add_i32 s18, s20, s42
	v_lshl_add_u64 v[174:175], v[174:175], 0, s[6:7]
	s_mov_b32 m0, s18
	s_nop 0
	global_load_lds_dwordx4 v[174:175], off
	v_lshl_add_u64 v[174:175], v[222:223], 0, s[6:7]
	s_add_i32 m0, s18, 0x2000
	s_nop 0
	global_load_lds_dwordx4 v[174:175], off
	s_mov_b32 m0, s50
	v_lshl_add_u64 v[174:175], v[224:225], 0, s[6:7]
	ds_read_b128 v[166:169], v173 offset:49152
	ds_read_b128 v[178:181], v173 offset:50176
	ds_read_b128 v[182:185], v173 offset:51200
	ds_read_b128 v[186:189], v173 offset:52224
	ds_read_b128 v[190:193], v173 offset:53248
	ds_read_b128 v[194:197], v173 offset:54272
	ds_read_b128 v[198:201], v173 offset:55296
	ds_read_b128 v[202:205], v173 offset:56320
	global_load_lds_dwordx4 v[174:175], off
	v_lshl_add_u64 v[174:175], v[226:227], 0, s[6:7]
	s_mov_b32 m0, s51
	s_nop 0
	global_load_lds_dwordx4 v[174:175], off
	s_add_u32 s18, s34, 0x40080
	s_addc_u32 s19, s35, 0
	s_add_i32 s20, s21, s42
	v_lshl_add_u64 v[252:253], s[18:19], 0, v[150:151]
	s_mov_b32 m0, s20
	s_nop 0
	global_load_lds_dwordx4 v[252:253], off
	v_lshl_add_u64 v[252:253], s[18:19], 0, v[146:147]
	s_add_i32 m0, s20, 0x2000
	s_nop 0
	global_load_lds_dwordx4 v[252:253], off
	s_waitcnt vmcnt(6)
	s_waitcnt lgkmcnt(0)
	s_setprio 1
	s_barrier
	v_mfma_f32_16x16x32_bf16 v[62:65], v[130:133], v[166:169], v[62:65]
	v_mfma_f32_16x16x32_bf16 v[58:61], v[138:141], v[166:169], v[58:61]
	v_mfma_f32_16x16x32_bf16 v[46:49], v[130:133], v[182:185], v[46:49]
	v_mfma_f32_16x16x32_bf16 v[42:45], v[138:141], v[182:185], v[42:45]
	v_mfma_f32_16x16x32_bf16 v[30:33], v[130:133], v[190:193], v[30:33]
	v_mfma_f32_16x16x32_bf16 v[26:29], v[138:141], v[190:193], v[26:29]
	v_mfma_f32_16x16x32_bf16 v[14:17], v[130:133], v[198:201], v[14:17]
	v_mfma_f32_16x16x32_bf16 v[10:13], v[138:141], v[198:201], v[10:13]
	v_mfma_f32_16x16x32_bf16 v[62:65], v[134:137], v[178:181], v[62:65]
	v_mfma_f32_16x16x32_bf16 v[58:61], v[142:145], v[178:181], v[58:61]
	v_mfma_f32_16x16x32_bf16 v[46:49], v[134:137], v[186:189], v[46:49]
	v_mfma_f32_16x16x32_bf16 v[42:45], v[142:145], v[186:189], v[42:45]
	v_mfma_f32_16x16x32_bf16 v[30:33], v[134:137], v[194:197], v[30:33]
	v_mfma_f32_16x16x32_bf16 v[26:29], v[142:145], v[194:197], v[26:29]
	v_mfma_f32_16x16x32_bf16 v[14:17], v[134:137], v[202:205], v[14:17]
	v_mfma_f32_16x16x32_bf16 v[10:13], v[142:145], v[202:205], v[10:13]
	v_mfma_f32_16x16x32_bf16 v[54:57], v[206:209], v[166:169], v[54:57]
	v_mfma_f32_16x16x32_bf16 v[50:53], v[214:217], v[166:169], v[50:53]
	v_mfma_f32_16x16x32_bf16 v[38:41], v[206:209], v[182:185], v[38:41]
	v_mfma_f32_16x16x32_bf16 v[34:37], v[214:217], v[182:185], v[34:37]
	v_mfma_f32_16x16x32_bf16 v[22:25], v[206:209], v[190:193], v[22:25]
	v_mfma_f32_16x16x32_bf16 v[18:21], v[214:217], v[190:193], v[18:21]
	v_mfma_f32_16x16x32_bf16 v[6:9], v[206:209], v[198:201], v[6:9]
	v_mfma_f32_16x16x32_bf16 v[2:5], v[214:217], v[198:201], v[2:5]
	v_mfma_f32_16x16x32_bf16 v[54:57], v[210:213], v[178:181], v[54:57]
	v_mfma_f32_16x16x32_bf16 v[50:53], v[218:221], v[178:181], v[50:53]
	v_mfma_f32_16x16x32_bf16 v[38:41], v[210:213], v[186:189], v[38:41]
	v_mfma_f32_16x16x32_bf16 v[34:37], v[218:221], v[186:189], v[34:37]
	v_mfma_f32_16x16x32_bf16 v[22:25], v[210:213], v[194:197], v[22:25]
	v_mfma_f32_16x16x32_bf16 v[18:21], v[218:221], v[194:197], v[18:21]
	v_mfma_f32_16x16x32_bf16 v[6:9], v[210:213], v[202:205], v[6:9]
	v_mfma_f32_16x16x32_bf16 v[2:5], v[218:221], v[202:205], v[2:5]
	s_barrier
	s_setprio 0
	s_add_i32 s63, s63, 2
	s_add_u32 s24, s24, 0x100
	s_addc_u32 s25, s25, 0
	s_add_u32 s61, s61, 0x100
	s_addc_u32 s62, s62, 0
	s_cmp_gt_u32 s63, 13
	s_cbranch_scc0 .LBB0_3265
	s_ashr_i32 s9, s16, 3
	s_mul_hi_i32 s11, s9, 0x5800
	s_mulk_i32 s9, 0x5800
	s_add_u32 s9, s48, s9
	s_addc_u32 s11, s49, s11
	s_lshl_b32 s18, s17, 8
	s_ashr_i32 s19, s18, 31
	s_lshl_b64 s[18:19], s[18:19], 2
	v_lshl_add_u32 v180, s16, 8, v1
	s_add_u32 s18, s9, s18
	s_addc_u32 s19, s11, s19
	v_lshlrev_b32_e32 v130, 2, v156
	v_ashrrev_i32_e32 v181, 31, v180
	v_mov_b32_e32 v142, v236
	v_mov_b32_e32 v143, v237
	v_mov_b32_e32 v144, v238
	v_mov_b32_e32 v145, v239
	v_lshl_add_u64 v[182:183], v[180:181], 2, s[4:5]
	v_mov_b32_e32 v190, v228
	v_mov_b32_e32 v138, v240
	v_mov_b32_e32 v139, v241
	v_mov_b32_e32 v140, v242
	v_mov_b32_e32 v141, v243
	v_mov_b32_e32 v134, v244
	v_mov_b32_e32 v135, v245
	v_mov_b32_e32 v136, v246
	v_mov_b32_e32 v137, v247
	s_nop 0
	v_mov_b32_e32 v130, v248
	v_mov_b32_e32 v131, v249
	v_mov_b32_e32 v132, v250
	v_mov_b32_e32 v133, v251
	v_or_b32_e32 v192, 16, v180
	v_ashrrev_i32_e32 v193, 31, v192
	v_lshl_add_u64 v[168:169], v[192:193], 2, s[4:5]
	v_mov_b32_e32 v194, v229
	v_or_b32_e32 v188, 32, v180
	v_or_b32_e32 v184, 48, v180
	v_mov_b64_e32 v[166:167], s[0:1]
	v_add_u32_e32 v178, 0x90, v180
	v_add_u32_e32 v174, 0xa0, v180
	v_add_u32_e32 v168, 0xb0, v180
	v_ashrrev_i32_e32 v189, 31, v188
	v_ashrrev_i32_e32 v185, 31, v184
	v_add_u32_e32 v193, 0x80, v180
	v_mad_i64_i32 v[196:197], s[18:19], v180, s56, v[166:167]
	v_ashrrev_i32_e32 v179, 31, v178
	v_ashrrev_i32_e32 v175, 31, v174
	v_ashrrev_i32_e32 v169, 31, v168
	v_lshl_add_u64 v[180:181], v[188:189], 2, s[4:5]
	v_lshl_add_u64 v[186:187], v[184:185], 2, s[4:5]
	v_lshl_add_u64 v[198:199], v[178:179], 2, s[4:5]
	v_lshl_add_u64 v[200:201], v[174:175], 2, s[4:5]
	v_lshl_add_u64 v[202:203], v[168:169], 2, s[4:5]
	v_mov_b32_e32 v204, v233
	s_nop 0
	v_mov_b32_e32 v186, v234
	s_nop 0
	v_mov_b32_e32 v180, v255
	s_nop 0
	v_mov_b32_e32 v182, v235
	s_lshl_b32 s16, s17, 7
	s_ashr_i32 s17, s16, 31
	s_lshl_b64 s[16:17], s[16:17], 1
	v_lshlrev_b32_e32 v154, 1, v156
	v_lshl_add_u64 v[196:197], v[196:197], 0, s[16:17]
	s_and_b64 vcc, exec, s[2:3]
	s_mov_b64 s[34:35], s[14:15]
	s_mov_b64 s[24:25], s[12:13]
	v_pk_fma_f32 v[118:119], v[118:119], v[190:191], v[138:139] op_sel_hi:[1,0,1]
	v_pk_fma_f32 v[126:127], v[126:127], v[190:191], v[142:143] op_sel_hi:[1,0,1]
	v_pk_fma_f32 v[128:129], v[128:129], v[190:191], v[144:145] op_sel_hi:[1,0,1]
	v_pk_fma_f32 v[122:123], v[122:123], v[190:191], v[134:135] op_sel_hi:[1,0,1]
	v_pk_fma_f32 v[124:125], v[124:125], v[190:191], v[136:137] op_sel_hi:[1,0,1]
	v_mul_f32_e32 v169, 0xbfb8aa3b, v126
	v_mul_f32_e32 v175, 0xbfb8aa3b, v127
	v_mul_f32_e32 v179, 0xbfb8aa3b, v128
	v_mul_f32_e32 v181, 0xbfb8aa3b, v129
	v_mul_f32_e32 v183, 0xbfb8aa3b, v122
	v_mul_f32_e32 v185, 0xbfb8aa3b, v123
	v_mul_f32_e32 v187, 0xbfb8aa3b, v124
	v_mul_f32_e32 v189, 0xbfb8aa3b, v125
	v_exp_f32_e32 v169, v169
	v_exp_f32_e32 v175, v175
	v_exp_f32_e32 v179, v179
	v_exp_f32_e32 v181, v181
	v_exp_f32_e32 v183, v183
	v_exp_f32_e32 v185, v185
	v_exp_f32_e32 v187, v187
	v_exp_f32_e32 v189, v189
	v_add_f32_e32 v169, 1.0, v169
	v_add_f32_e32 v175, 1.0, v175
	v_add_f32_e32 v179, 1.0, v179
	v_add_f32_e32 v181, 1.0, v181
	v_add_f32_e32 v183, 1.0, v183
	v_add_f32_e32 v185, 1.0, v185
	v_add_f32_e32 v187, 1.0, v187
	v_add_f32_e32 v189, 1.0, v189
	v_pk_fma_f32 v[120:121], v[120:121], v[190:191], v[140:141] op_sel_hi:[1,0,1]
	v_pk_fma_f32 v[114:115], v[114:115], v[190:191], v[130:131] op_sel_hi:[1,0,1]
	v_pk_fma_f32 v[116:117], v[116:117], v[190:191], v[132:133] op_sel_hi:[1,0,1]
	v_rcp_f32_e32 v190, v169
	v_rcp_f32_e32 v191, v175
	v_rcp_f32_e32 v198, v179
	v_rcp_f32_e32 v199, v181
	v_rcp_f32_e32 v200, v183
	v_rcp_f32_e32 v201, v185
	v_rcp_f32_e32 v202, v187
	v_rcp_f32_e32 v203, v189
	v_pk_mul_f32 v[126:127], v[126:127], v[190:191]
	v_pk_mul_f32 v[128:129], v[128:129], v[198:199]
	v_pk_mul_f32 v[122:123], v[122:123], v[200:201]
	v_pk_mul_f32 v[124:125], v[124:125], v[202:203]
	v_pk_mul_f32 v[118:119], v[118:119], v[126:127]
	v_pk_mul_f32 v[120:121], v[120:121], v[128:129]
	v_pk_mul_f32 v[122:123], v[114:115], v[122:123]
	v_pk_mul_f32 v[124:125], v[116:117], v[124:125]
	v_pk_fma_f32 v[110:111], v[110:111], v[194:195], v[142:143] op_sel_hi:[1,0,1]
	v_lshl_add_u64 v[126:127], v[196:197], 0, v[154:155]
	v_cvt_pk_bf16_f32 v114, v118, v119
	v_cvt_pk_bf16_f32 v115, v120, v121
	v_cvt_pk_bf16_f32 v116, v122, v123
	v_cvt_pk_bf16_f32 v117, v124, v125
	v_mul_f32_e32 v118, 0xbfb8aa3b, v110
	v_mul_f32_e32 v119, 0xbfb8aa3b, v111
	v_pk_fma_f32 v[112:113], v[112:113], v[194:195], v[144:145] op_sel_hi:[1,0,1]
	v_exp_f32_e32 v118, v118
	v_exp_f32_e32 v119, v119
	global_store_dwordx4 v[126:127], v[114:117], off nt
	v_pk_fma_f32 v[102:103], v[102:103], v[194:195], v[138:139] op_sel_hi:[1,0,1]
	v_pk_fma_f32 v[106:107], v[106:107], v[194:195], v[134:135] op_sel_hi:[1,0,1]
	v_mul_f32_e32 v116, 0xbfb8aa3b, v112
	v_mul_f32_e32 v117, 0xbfb8aa3b, v113
	v_exp_f32_e32 v116, v116
	v_exp_f32_e32 v117, v117
	v_add_f32_e32 v114, 1.0, v118
	v_add_f32_e32 v115, 1.0, v119
	v_rcp_f32_e32 v114, v114
	v_rcp_f32_e32 v115, v115
	v_add_f32_e32 v116, 1.0, v116
	v_add_f32_e32 v117, 1.0, v117
	v_rcp_f32_e32 v116, v116
	v_rcp_f32_e32 v117, v117
	v_pk_mul_f32 v[110:111], v[110:111], v[114:115]
	v_pk_fma_f32 v[104:105], v[104:105], v[194:195], v[140:141] op_sel_hi:[1,0,1]
	v_pk_mul_f32 v[102:103], v[102:103], v[110:111]
	v_pk_mul_f32 v[110:111], v[112:113], v[116:117]
	v_mul_f32_e32 v112, 0xbfb8aa3b, v106
	v_mul_f32_e32 v113, 0xbfb8aa3b, v107
	v_exp_f32_e32 v112, v112
	v_exp_f32_e32 v113, v113
	v_pk_fma_f32 v[108:109], v[108:109], v[194:195], v[136:137] op_sel_hi:[1,0,1]
	v_pk_mul_f32 v[104:105], v[104:105], v[110:111]
	v_add_f32_e32 v110, 1.0, v112
	v_add_f32_e32 v111, 1.0, v113
	v_mul_f32_e32 v112, 0xbfb8aa3b, v108
	v_mul_f32_e32 v113, 0xbfb8aa3b, v109
	v_exp_f32_e32 v112, v112
	v_exp_f32_e32 v113, v113
	v_rcp_f32_e32 v110, v110
	v_rcp_f32_e32 v111, v111
	v_add_f32_e32 v112, 1.0, v112
	v_add_f32_e32 v113, 1.0, v113
	v_rcp_f32_e32 v112, v112
	v_rcp_f32_e32 v113, v113
	v_pk_mul_f32 v[106:107], v[106:107], v[110:111]
	v_pk_fma_f32 v[98:99], v[98:99], v[194:195], v[130:131] op_sel_hi:[1,0,1]
	v_pk_fma_f32 v[100:101], v[100:101], v[194:195], v[132:133] op_sel_hi:[1,0,1]
	v_pk_mul_f32 v[106:107], v[98:99], v[106:107]
	v_pk_mul_f32 v[98:99], v[108:109], v[112:113]
	v_pk_fma_f32 v[94:95], v[94:95], v[204:205], v[142:143] op_sel_hi:[1,0,1]
	v_pk_mul_f32 v[108:109], v[100:101], v[98:99]
	v_mad_i64_i32 v[98:99], s[18:19], v192, s56, v[166:167]
	v_lshl_add_u64 v[98:99], v[98:99], 0, s[16:17]
	v_lshl_add_u64 v[110:111], v[98:99], 0, v[154:155]
	v_cvt_pk_bf16_f32 v98, v102, v103
	v_cvt_pk_bf16_f32 v99, v104, v105
	v_cvt_pk_bf16_f32 v100, v106, v107
	v_cvt_pk_bf16_f32 v101, v108, v109
	v_mul_f32_e32 v102, 0xbfb8aa3b, v94
	v_mul_f32_e32 v103, 0xbfb8aa3b, v95
	v_pk_fma_f32 v[96:97], v[96:97], v[204:205], v[144:145] op_sel_hi:[1,0,1]
	v_exp_f32_e32 v102, v102
	v_exp_f32_e32 v103, v103
	global_store_dwordx4 v[110:111], v[98:101], off nt
	v_pk_fma_f32 v[86:87], v[86:87], v[204:205], v[138:139] op_sel_hi:[1,0,1]
	v_pk_fma_f32 v[90:91], v[90:91], v[204:205], v[134:135] op_sel_hi:[1,0,1]
	v_mul_f32_e32 v100, 0xbfb8aa3b, v96
	v_mul_f32_e32 v101, 0xbfb8aa3b, v97
	v_exp_f32_e32 v100, v100
	v_exp_f32_e32 v101, v101
	v_add_f32_e32 v98, 1.0, v102
	v_add_f32_e32 v99, 1.0, v103
	v_rcp_f32_e32 v98, v98
	v_rcp_f32_e32 v99, v99
	v_add_f32_e32 v100, 1.0, v100
	v_add_f32_e32 v101, 1.0, v101
	v_rcp_f32_e32 v100, v100
	v_rcp_f32_e32 v101, v101
	v_pk_mul_f32 v[94:95], v[94:95], v[98:99]
	v_pk_fma_f32 v[88:89], v[88:89], v[204:205], v[140:141] op_sel_hi:[1,0,1]
	v_pk_mul_f32 v[86:87], v[86:87], v[94:95]
	v_pk_mul_f32 v[94:95], v[96:97], v[100:101]
	v_mul_f32_e32 v96, 0xbfb8aa3b, v90
	v_mul_f32_e32 v97, 0xbfb8aa3b, v91
	v_exp_f32_e32 v96, v96
	v_exp_f32_e32 v97, v97
	v_pk_fma_f32 v[92:93], v[92:93], v[204:205], v[136:137] op_sel_hi:[1,0,1]
	v_pk_mul_f32 v[88:89], v[88:89], v[94:95]
	v_add_f32_e32 v94, 1.0, v96
	v_add_f32_e32 v95, 1.0, v97
	v_mul_f32_e32 v96, 0xbfb8aa3b, v92
	v_mul_f32_e32 v97, 0xbfb8aa3b, v93
	v_exp_f32_e32 v96, v96
	v_exp_f32_e32 v97, v97
	v_rcp_f32_e32 v94, v94
	v_rcp_f32_e32 v95, v95
	v_add_f32_e32 v96, 1.0, v96
	v_add_f32_e32 v97, 1.0, v97
	v_rcp_f32_e32 v96, v96
	v_rcp_f32_e32 v97, v97
	v_pk_mul_f32 v[90:91], v[90:91], v[94:95]
	v_pk_fma_f32 v[82:83], v[82:83], v[204:205], v[130:131] op_sel_hi:[1,0,1]
	v_pk_fma_f32 v[84:85], v[84:85], v[204:205], v[132:133] op_sel_hi:[1,0,1]
	v_pk_mul_f32 v[90:91], v[82:83], v[90:91]
	v_pk_mul_f32 v[82:83], v[92:93], v[96:97]
	v_pk_fma_f32 v[78:79], v[78:79], v[186:187], v[142:143] op_sel_hi:[1,0,1]
	v_pk_mul_f32 v[92:93], v[84:85], v[82:83]
	v_mad_i64_i32 v[82:83], s[18:19], v188, s56, v[166:167]
	v_lshl_add_u64 v[82:83], v[82:83], 0, s[16:17]
	v_lshl_add_u64 v[94:95], v[82:83], 0, v[154:155]
	v_cvt_pk_bf16_f32 v82, v86, v87
	v_cvt_pk_bf16_f32 v83, v88, v89
	v_cvt_pk_bf16_f32 v84, v90, v91
	v_cvt_pk_bf16_f32 v85, v92, v93
	v_mul_f32_e32 v86, 0xbfb8aa3b, v78
	v_mul_f32_e32 v87, 0xbfb8aa3b, v79
	v_pk_fma_f32 v[80:81], v[80:81], v[186:187], v[144:145] op_sel_hi:[1,0,1]
	v_exp_f32_e32 v86, v86
	v_exp_f32_e32 v87, v87
	global_store_dwordx4 v[94:95], v[82:85], off nt
	v_pk_fma_f32 v[70:71], v[70:71], v[186:187], v[138:139] op_sel_hi:[1,0,1]
	v_pk_fma_f32 v[74:75], v[74:75], v[186:187], v[134:135] op_sel_hi:[1,0,1]
	v_mul_f32_e32 v84, 0xbfb8aa3b, v80
	v_mul_f32_e32 v85, 0xbfb8aa3b, v81
	v_exp_f32_e32 v84, v84
	v_exp_f32_e32 v85, v85
	v_add_f32_e32 v82, 1.0, v86
	v_add_f32_e32 v83, 1.0, v87
	v_rcp_f32_e32 v82, v82
	v_rcp_f32_e32 v83, v83
	v_add_f32_e32 v84, 1.0, v84
	v_add_f32_e32 v85, 1.0, v85
	v_rcp_f32_e32 v84, v84
	v_rcp_f32_e32 v85, v85
	v_pk_mul_f32 v[78:79], v[78:79], v[82:83]
	v_pk_fma_f32 v[72:73], v[72:73], v[186:187], v[140:141] op_sel_hi:[1,0,1]
	v_pk_mul_f32 v[70:71], v[70:71], v[78:79]
	v_pk_mul_f32 v[78:79], v[80:81], v[84:85]
	v_mul_f32_e32 v80, 0xbfb8aa3b, v74
	v_mul_f32_e32 v81, 0xbfb8aa3b, v75
	v_exp_f32_e32 v80, v80
	v_exp_f32_e32 v81, v81
	v_pk_fma_f32 v[76:77], v[76:77], v[186:187], v[136:137] op_sel_hi:[1,0,1]
	v_pk_mul_f32 v[72:73], v[72:73], v[78:79]
	v_add_f32_e32 v78, 1.0, v80
	v_add_f32_e32 v79, 1.0, v81
	v_mul_f32_e32 v80, 0xbfb8aa3b, v76
	v_mul_f32_e32 v81, 0xbfb8aa3b, v77
	v_exp_f32_e32 v80, v80
	v_exp_f32_e32 v81, v81
	v_rcp_f32_e32 v78, v78
	v_rcp_f32_e32 v79, v79
	v_add_f32_e32 v80, 1.0, v80
	v_add_f32_e32 v81, 1.0, v81
	v_rcp_f32_e32 v80, v80
	v_rcp_f32_e32 v81, v81
	v_pk_mul_f32 v[74:75], v[74:75], v[78:79]
	v_pk_fma_f32 v[66:67], v[66:67], v[186:187], v[130:131] op_sel_hi:[1,0,1]
	v_pk_fma_f32 v[68:69], v[68:69], v[186:187], v[132:133] op_sel_hi:[1,0,1]
	v_pk_mul_f32 v[74:75], v[66:67], v[74:75]
	v_pk_mul_f32 v[66:67], v[76:77], v[80:81]
	v_pk_fma_f32 v[62:63], v[62:63], v[182:183], v[142:143] op_sel_hi:[1,0,1]
	v_pk_mul_f32 v[76:77], v[68:69], v[66:67]
	v_mad_i64_i32 v[66:67], s[18:19], v184, s56, v[166:167]
	v_lshl_add_u64 v[66:67], v[66:67], 0, s[16:17]
	v_lshl_add_u64 v[78:79], v[66:67], 0, v[154:155]
	v_cvt_pk_bf16_f32 v66, v70, v71
	v_cvt_pk_bf16_f32 v67, v72, v73
	v_cvt_pk_bf16_f32 v68, v74, v75
	v_cvt_pk_bf16_f32 v69, v76, v77
	v_mul_f32_e32 v70, 0xbfb8aa3b, v62
	v_mul_f32_e32 v71, 0xbfb8aa3b, v63
	v_pk_fma_f32 v[64:65], v[64:65], v[182:183], v[144:145] op_sel_hi:[1,0,1]
	v_exp_f32_e32 v70, v70
	v_exp_f32_e32 v71, v71
	global_store_dwordx4 v[78:79], v[66:69], off nt
	v_pk_fma_f32 v[54:55], v[54:55], v[182:183], v[138:139] op_sel_hi:[1,0,1]
	v_pk_fma_f32 v[58:59], v[58:59], v[182:183], v[134:135] op_sel_hi:[1,0,1]
	v_mul_f32_e32 v68, 0xbfb8aa3b, v64
	v_mul_f32_e32 v69, 0xbfb8aa3b, v65
	v_exp_f32_e32 v68, v68
	v_exp_f32_e32 v69, v69
	v_add_f32_e32 v66, 1.0, v70
	v_add_f32_e32 v67, 1.0, v71
	v_rcp_f32_e32 v66, v66
	v_rcp_f32_e32 v67, v67
	v_add_f32_e32 v68, 1.0, v68
	v_add_f32_e32 v69, 1.0, v69
	v_rcp_f32_e32 v68, v68
	v_rcp_f32_e32 v69, v69
	v_pk_mul_f32 v[62:63], v[62:63], v[66:67]
	v_pk_fma_f32 v[56:57], v[56:57], v[182:183], v[140:141] op_sel_hi:[1,0,1]
	v_pk_mul_f32 v[54:55], v[54:55], v[62:63]
	v_pk_mul_f32 v[62:63], v[64:65], v[68:69]
	v_mul_f32_e32 v64, 0xbfb8aa3b, v58
	v_mul_f32_e32 v65, 0xbfb8aa3b, v59
	v_exp_f32_e32 v64, v64
	v_exp_f32_e32 v65, v65
	v_pk_fma_f32 v[60:61], v[60:61], v[182:183], v[136:137] op_sel_hi:[1,0,1]
	v_pk_mul_f32 v[56:57], v[56:57], v[62:63]
	v_add_f32_e32 v62, 1.0, v64
	v_add_f32_e32 v63, 1.0, v65
	v_mul_f32_e32 v64, 0xbfb8aa3b, v60
	v_mul_f32_e32 v65, 0xbfb8aa3b, v61
	v_exp_f32_e32 v64, v64
	v_exp_f32_e32 v65, v65
	v_rcp_f32_e32 v62, v62
	v_rcp_f32_e32 v63, v63
	v_add_f32_e32 v64, 1.0, v64
	v_add_f32_e32 v65, 1.0, v65
	v_rcp_f32_e32 v64, v64
	v_rcp_f32_e32 v65, v65
	v_pk_mul_f32 v[58:59], v[58:59], v[62:63]
	v_pk_fma_f32 v[50:51], v[50:51], v[182:183], v[130:131] op_sel_hi:[1,0,1]
	v_pk_fma_f32 v[52:53], v[52:53], v[182:183], v[132:133] op_sel_hi:[1,0,1]
	v_pk_mul_f32 v[58:59], v[50:51], v[58:59]
	v_pk_mul_f32 v[50:51], v[60:61], v[64:65]
	v_pk_fma_f32 v[46:47], v[46:47], v[180:181], v[142:143] op_sel_hi:[1,0,1]
	v_pk_mul_f32 v[60:61], v[52:53], v[50:51]
	v_mad_i64_i32 v[50:51], s[18:19], v193, s56, v[166:167]
	v_lshl_add_u64 v[50:51], v[50:51], 0, s[16:17]
	v_lshl_add_u64 v[62:63], v[50:51], 0, v[154:155]
	v_cvt_pk_bf16_f32 v50, v54, v55
	v_cvt_pk_bf16_f32 v51, v56, v57
	v_cvt_pk_bf16_f32 v52, v58, v59
	v_cvt_pk_bf16_f32 v53, v60, v61
	v_mul_f32_e32 v54, 0xbfb8aa3b, v46
	v_mul_f32_e32 v55, 0xbfb8aa3b, v47
	v_pk_fma_f32 v[48:49], v[48:49], v[180:181], v[144:145] op_sel_hi:[1,0,1]
	v_exp_f32_e32 v54, v54
	v_exp_f32_e32 v55, v55
	global_store_dwordx4 v[62:63], v[50:53], off nt
	v_pk_fma_f32 v[38:39], v[38:39], v[180:181], v[138:139] op_sel_hi:[1,0,1]
	v_pk_fma_f32 v[42:43], v[42:43], v[180:181], v[134:135] op_sel_hi:[1,0,1]
	v_mul_f32_e32 v52, 0xbfb8aa3b, v48
	v_mul_f32_e32 v53, 0xbfb8aa3b, v49
	v_exp_f32_e32 v52, v52
	v_exp_f32_e32 v53, v53
	v_add_f32_e32 v50, 1.0, v54
	v_add_f32_e32 v51, 1.0, v55
	v_rcp_f32_e32 v50, v50
	v_rcp_f32_e32 v51, v51
	v_add_f32_e32 v52, 1.0, v52
	v_add_f32_e32 v53, 1.0, v53
	v_rcp_f32_e32 v52, v52
	v_rcp_f32_e32 v53, v53
	v_pk_mul_f32 v[46:47], v[46:47], v[50:51]
	v_pk_fma_f32 v[40:41], v[40:41], v[180:181], v[140:141] op_sel_hi:[1,0,1]
	v_pk_mul_f32 v[38:39], v[38:39], v[46:47]
	v_pk_mul_f32 v[46:47], v[48:49], v[52:53]
	v_mul_f32_e32 v48, 0xbfb8aa3b, v42
	v_mul_f32_e32 v49, 0xbfb8aa3b, v43
	v_exp_f32_e32 v48, v48
	v_exp_f32_e32 v49, v49
	v_pk_fma_f32 v[44:45], v[44:45], v[180:181], v[136:137] op_sel_hi:[1,0,1]
	v_pk_mul_f32 v[40:41], v[40:41], v[46:47]
	v_add_f32_e32 v46, 1.0, v48
	v_add_f32_e32 v47, 1.0, v49
	v_mul_f32_e32 v48, 0xbfb8aa3b, v44
	v_mul_f32_e32 v49, 0xbfb8aa3b, v45
	v_exp_f32_e32 v48, v48
	v_exp_f32_e32 v49, v49
	v_rcp_f32_e32 v46, v46
	v_rcp_f32_e32 v47, v47
	v_add_f32_e32 v48, 1.0, v48
	v_add_f32_e32 v49, 1.0, v49
	v_rcp_f32_e32 v48, v48
	v_rcp_f32_e32 v49, v49
	v_pk_mul_f32 v[42:43], v[42:43], v[46:47]
	v_pk_fma_f32 v[34:35], v[34:35], v[180:181], v[130:131] op_sel_hi:[1,0,1]
	v_pk_fma_f32 v[36:37], v[36:37], v[180:181], v[132:133] op_sel_hi:[1,0,1]
	v_pk_mul_f32 v[42:43], v[34:35], v[42:43]
	v_pk_mul_f32 v[34:35], v[44:45], v[48:49]
	v_pk_fma_f32 v[30:31], v[30:31], v[176:177], v[142:143] op_sel_hi:[1,0,1]
	v_pk_mul_f32 v[44:45], v[36:37], v[34:35]
	v_mad_i64_i32 v[34:35], s[18:19], v178, s56, v[166:167]
	v_lshl_add_u64 v[34:35], v[34:35], 0, s[16:17]
	v_lshl_add_u64 v[46:47], v[34:35], 0, v[154:155]
	v_cvt_pk_bf16_f32 v34, v38, v39
	v_cvt_pk_bf16_f32 v35, v40, v41
	v_cvt_pk_bf16_f32 v36, v42, v43
	v_cvt_pk_bf16_f32 v37, v44, v45
	v_mul_f32_e32 v38, 0xbfb8aa3b, v30
	v_mul_f32_e32 v39, 0xbfb8aa3b, v31
	v_pk_fma_f32 v[32:33], v[32:33], v[176:177], v[144:145] op_sel_hi:[1,0,1]
	v_exp_f32_e32 v38, v38
	v_exp_f32_e32 v39, v39
	global_store_dwordx4 v[46:47], v[34:37], off nt
	v_pk_fma_f32 v[22:23], v[22:23], v[176:177], v[138:139] op_sel_hi:[1,0,1]
	v_pk_fma_f32 v[26:27], v[26:27], v[176:177], v[134:135] op_sel_hi:[1,0,1]
	v_mul_f32_e32 v36, 0xbfb8aa3b, v32
	v_mul_f32_e32 v37, 0xbfb8aa3b, v33
	v_exp_f32_e32 v36, v36
	v_exp_f32_e32 v37, v37
	v_add_f32_e32 v34, 1.0, v38
	v_add_f32_e32 v35, 1.0, v39
	v_rcp_f32_e32 v34, v34
	v_rcp_f32_e32 v35, v35
	v_add_f32_e32 v36, 1.0, v36
	v_add_f32_e32 v37, 1.0, v37
	v_rcp_f32_e32 v36, v36
	v_rcp_f32_e32 v37, v37
	v_pk_mul_f32 v[30:31], v[30:31], v[34:35]
	v_pk_fma_f32 v[24:25], v[24:25], v[176:177], v[140:141] op_sel_hi:[1,0,1]
	v_pk_mul_f32 v[22:23], v[22:23], v[30:31]
	v_pk_mul_f32 v[30:31], v[32:33], v[36:37]
	v_mul_f32_e32 v32, 0xbfb8aa3b, v26
	v_mul_f32_e32 v33, 0xbfb8aa3b, v27
	v_exp_f32_e32 v32, v32
	v_exp_f32_e32 v33, v33
	v_pk_fma_f32 v[28:29], v[28:29], v[176:177], v[136:137] op_sel_hi:[1,0,1]
	v_pk_mul_f32 v[24:25], v[24:25], v[30:31]
	v_add_f32_e32 v30, 1.0, v32
	v_add_f32_e32 v31, 1.0, v33
	v_mul_f32_e32 v32, 0xbfb8aa3b, v28
	v_mul_f32_e32 v33, 0xbfb8aa3b, v29
	v_exp_f32_e32 v32, v32
	v_exp_f32_e32 v33, v33
	v_rcp_f32_e32 v30, v30
	v_rcp_f32_e32 v31, v31
	v_add_f32_e32 v32, 1.0, v32
	v_add_f32_e32 v33, 1.0, v33
	v_rcp_f32_e32 v32, v32
	v_rcp_f32_e32 v33, v33
	v_pk_mul_f32 v[26:27], v[26:27], v[30:31]
	v_pk_fma_f32 v[18:19], v[18:19], v[176:177], v[130:131] op_sel_hi:[1,0,1]
	v_pk_fma_f32 v[20:21], v[20:21], v[176:177], v[132:133] op_sel_hi:[1,0,1]
	v_pk_mul_f32 v[26:27], v[18:19], v[26:27]
	v_pk_mul_f32 v[18:19], v[28:29], v[32:33]
	v_pk_fma_f32 v[14:15], v[14:15], v[172:173], v[142:143] op_sel_hi:[1,0,1]
	v_pk_mul_f32 v[28:29], v[20:21], v[18:19]
	v_mad_i64_i32 v[18:19], s[18:19], v174, s56, v[166:167]
	v_lshl_add_u64 v[18:19], v[18:19], 0, s[16:17]
	v_lshl_add_u64 v[30:31], v[18:19], 0, v[154:155]
	v_cvt_pk_bf16_f32 v18, v22, v23
	v_cvt_pk_bf16_f32 v19, v24, v25
	v_cvt_pk_bf16_f32 v20, v26, v27
	v_cvt_pk_bf16_f32 v21, v28, v29
	v_mul_f32_e32 v22, 0xbfb8aa3b, v14
	v_mul_f32_e32 v23, 0xbfb8aa3b, v15
	v_pk_fma_f32 v[16:17], v[16:17], v[172:173], v[144:145] op_sel_hi:[1,0,1]
	v_exp_f32_e32 v22, v22
	v_exp_f32_e32 v23, v23
	global_store_dwordx4 v[30:31], v[18:21], off nt
	v_pk_fma_f32 v[6:7], v[6:7], v[172:173], v[138:139] op_sel_hi:[1,0,1]
	v_pk_fma_f32 v[10:11], v[10:11], v[172:173], v[134:135] op_sel_hi:[1,0,1]
	v_mul_f32_e32 v20, 0xbfb8aa3b, v16
	v_mul_f32_e32 v21, 0xbfb8aa3b, v17
	v_exp_f32_e32 v20, v20
	v_exp_f32_e32 v21, v21
	v_add_f32_e32 v18, 1.0, v22
	v_add_f32_e32 v19, 1.0, v23
	v_rcp_f32_e32 v18, v18
	v_rcp_f32_e32 v19, v19
	v_add_f32_e32 v20, 1.0, v20
	v_add_f32_e32 v21, 1.0, v21
	v_rcp_f32_e32 v20, v20
	v_rcp_f32_e32 v21, v21
	v_pk_mul_f32 v[14:15], v[14:15], v[18:19]
	v_pk_fma_f32 v[8:9], v[8:9], v[172:173], v[140:141] op_sel_hi:[1,0,1]
	v_pk_mul_f32 v[6:7], v[6:7], v[14:15]
	v_pk_mul_f32 v[14:15], v[16:17], v[20:21]
	v_mul_f32_e32 v16, 0xbfb8aa3b, v10
	v_mul_f32_e32 v17, 0xbfb8aa3b, v11
	v_exp_f32_e32 v16, v16
	v_exp_f32_e32 v17, v17
	v_pk_fma_f32 v[12:13], v[12:13], v[172:173], v[136:137] op_sel_hi:[1,0,1]
	v_pk_mul_f32 v[8:9], v[8:9], v[14:15]
	v_add_f32_e32 v14, 1.0, v16
	v_add_f32_e32 v15, 1.0, v17
	v_mul_f32_e32 v16, 0xbfb8aa3b, v12
	v_mul_f32_e32 v17, 0xbfb8aa3b, v13
	v_exp_f32_e32 v16, v16
	v_exp_f32_e32 v17, v17
	v_rcp_f32_e32 v14, v14
	v_rcp_f32_e32 v15, v15
	v_add_f32_e32 v16, 1.0, v16
	v_add_f32_e32 v17, 1.0, v17
	v_rcp_f32_e32 v16, v16
	v_rcp_f32_e32 v17, v17
	v_pk_mul_f32 v[10:11], v[10:11], v[14:15]
	v_pk_fma_f32 v[2:3], v[2:3], v[172:173], v[130:131] op_sel_hi:[1,0,1]
	v_pk_fma_f32 v[4:5], v[4:5], v[172:173], v[132:133] op_sel_hi:[1,0,1]
	v_pk_mul_f32 v[10:11], v[2:3], v[10:11]
	v_pk_mul_f32 v[2:3], v[12:13], v[16:17]
	s_nop 0
	v_pk_mul_f32 v[12:13], v[4:5], v[2:3]
	v_mad_i64_i32 v[2:3], s[18:19], v168, s56, v[166:167]
	v_lshl_add_u64 v[2:3], v[2:3], 0, s[16:17]
	v_lshl_add_u64 v[14:15], v[2:3], 0, v[154:155]
	v_cvt_pk_bf16_f32 v2, v6, v7
	v_cvt_pk_bf16_f32 v3, v8, v9
	v_cvt_pk_bf16_f32 v4, v10, v11
	v_cvt_pk_bf16_f32 v5, v12, v13
	s_mov_b32 s17, s8
	s_mov_b32 s16, s10
	global_store_dwordx4 v[14:15], v[2:5], off nt
	s_cbranch_vccz .LBB0_3262
	s_waitcnt vmcnt(0)
	s_cmpk_gt_u32 s33, 0xff
	s_cbranch_scc1 .LBB0_3269
	s_barrier
